# same-accumulator k0/k1 MFMA pairs issued back-to-back (accumulate chain), snake order over fragment pairs
# speedup vs baseline: 1.0270x; 1.0067x over previous
.LBB0_169:
	s_add_u32 s34, s50, 0xfff80080
	s_addc_u32 s35, s51, -1
	s_add_i32 s52, 0, 0x10000
	s_cmp_eq_u32 s77, 28
	s_cselect_b32 s55, s36, s35
	s_cselect_b32 s54, s37, s34
	v_add_u32_e32 v145, s52, v142
	s_cselect_b32 s35, s41, s76
	s_cselect_b32 s34, s43, s71
	s_add_i32 s53, 0, 0x14000
	ds_read_b128 v[146:149], v145
	ds_read_b128 v[150:153], v145 offset:1024
	ds_read_b128 v[172:175], v145 offset:2048
	ds_read_b128 v[176:179], v145 offset:3072
	v_add_u32_e32 v145, s53, v142
	ds_read_b128 v[180:183], v145
	ds_read_b128 v[184:187], v145 offset:1024
	ds_read_b128 v[188:191], v145 offset:2048
	ds_read_b128 v[192:195], v145 offset:3072
	v_lshl_add_u64 v[154:155], s[50:51], 0, v[138:139]
	s_add_i32 m0, s57, 0xc000
	ds_read_b128 v[196:199], v144
	ds_read_b128 v[200:203], v144 offset:1024
	ds_read_b128 v[204:207], v144 offset:2048
	ds_read_b128 v[208:211], v144 offset:3072
	ds_read_b128 v[212:215], v144 offset:4096
	ds_read_b128 v[216:219], v144 offset:5120
	ds_read_b128 v[228:231], v144 offset:6144
	ds_read_b128 v[232:235], v144 offset:7168
	global_load_lds_dwordx4 v[154:155], off
	v_lshl_add_u64 v[154:155], s[50:51], 0, v[140:141]
	s_add_i32 m0, s57, 0xe000
	s_nop 0
	global_load_lds_dwordx4 v[154:155], off
	s_waitcnt vmcnt(8)
	s_waitcnt lgkmcnt(0)
	s_barrier
	s_setprio 1
	v_mfma_f32_16x16x32_bf16 v[128:131], v[146:149], v[196:199], v[128:131]
	v_mfma_f32_16x16x32_bf16 v[128:131], v[150:153], v[200:203], v[128:131]
	v_mfma_f32_16x16x32_bf16 v[124:127], v[172:175], v[196:199], v[124:127]
	v_mfma_f32_16x16x32_bf16 v[124:127], v[176:179], v[200:203], v[124:127]
	v_mfma_f32_16x16x32_bf16 v[108:111], v[172:175], v[204:207], v[108:111]
	v_mfma_f32_16x16x32_bf16 v[108:111], v[176:179], v[208:211], v[108:111]
	v_mfma_f32_16x16x32_bf16 v[112:115], v[146:149], v[204:207], v[112:115]
	v_mfma_f32_16x16x32_bf16 v[112:115], v[150:153], v[208:211], v[112:115]
	v_mfma_f32_16x16x32_bf16 v[96:99], v[146:149], v[212:215], v[96:99]
	v_mfma_f32_16x16x32_bf16 v[96:99], v[150:153], v[216:219], v[96:99]
	v_mfma_f32_16x16x32_bf16 v[92:95], v[172:175], v[212:215], v[92:95]
	v_mfma_f32_16x16x32_bf16 v[92:95], v[176:179], v[216:219], v[92:95]
	v_mfma_f32_16x16x32_bf16 v[76:79], v[172:175], v[228:231], v[76:79]
	v_mfma_f32_16x16x32_bf16 v[76:79], v[176:179], v[232:235], v[76:79]
	v_mfma_f32_16x16x32_bf16 v[80:83], v[146:149], v[228:231], v[80:83]
	v_mfma_f32_16x16x32_bf16 v[80:83], v[150:153], v[232:235], v[80:83]
	v_mfma_f32_16x16x32_bf16 v[120:123], v[180:183], v[196:199], v[120:123]
	v_mfma_f32_16x16x32_bf16 v[120:123], v[184:187], v[200:203], v[120:123]
	v_mfma_f32_16x16x32_bf16 v[116:119], v[188:191], v[196:199], v[116:119]
	v_mfma_f32_16x16x32_bf16 v[116:119], v[192:195], v[200:203], v[116:119]
	v_mfma_f32_16x16x32_bf16 v[100:103], v[188:191], v[204:207], v[100:103]
	v_mfma_f32_16x16x32_bf16 v[100:103], v[192:195], v[208:211], v[100:103]
	v_mfma_f32_16x16x32_bf16 v[104:107], v[180:183], v[204:207], v[104:107]
	v_mfma_f32_16x16x32_bf16 v[104:107], v[184:187], v[208:211], v[104:107]
	v_mfma_f32_16x16x32_bf16 v[88:91], v[180:183], v[212:215], v[88:91]
	v_mfma_f32_16x16x32_bf16 v[88:91], v[184:187], v[216:219], v[88:91]
	v_mfma_f32_16x16x32_bf16 v[84:87], v[188:191], v[212:215], v[84:87]
	v_mfma_f32_16x16x32_bf16 v[84:87], v[192:195], v[216:219], v[84:87]
	v_mfma_f32_16x16x32_bf16 v[68:71], v[188:191], v[228:231], v[68:71]
	v_mfma_f32_16x16x32_bf16 v[68:71], v[192:195], v[232:235], v[68:71]
	v_mfma_f32_16x16x32_bf16 v[72:75], v[180:183], v[228:231], v[72:75]
	v_mfma_f32_16x16x32_bf16 v[72:75], v[184:187], v[232:235], v[72:75]
	s_setprio 0
	s_barrier
	s_add_i32 s52, s52, s19
	v_lshl_add_u64 v[154:155], s[34:35], 0, v[134:135]
	s_mov_b32 m0, s52
	ds_read_b128 v[196:199], v144 offset:16384
	ds_read_b128 v[200:203], v144 offset:17408
	ds_read_b128 v[204:207], v144 offset:18432
	ds_read_b128 v[208:211], v144 offset:19456
	ds_read_b128 v[212:215], v144 offset:20480
	ds_read_b128 v[216:219], v144 offset:21504
	ds_read_b128 v[228:231], v144 offset:22528
	ds_read_b128 v[232:235], v144 offset:23552
	global_load_lds_dwordx4 v[154:155], off
	s_add_i32 m0, s52, 0x2000
	s_add_u32 s96, s34, 0x4000
	v_lshl_add_u64 v[154:155], s[34:35], 0, v[0:1]
	s_addc_u32 s97, s35, 0
	s_add_i32 s52, s53, s19
	global_load_lds_dwordx4 v[154:155], off
	v_lshl_add_u64 v[154:155], s[96:97], 0, v[134:135]
	s_mov_b32 m0, s52
	v_lshl_add_u64 v[236:237], s[54:55], 0, v[132:133]
	global_load_lds_dwordx4 v[154:155], off
	v_lshl_add_u64 v[154:155], s[96:97], 0, v[0:1]
	s_add_i32 m0, s52, 0x2000
	s_nop 0
	global_load_lds_dwordx4 v[154:155], off
	v_lshl_add_u64 v[154:155], s[54:55], 0, v[136:137]
	s_mov_b32 m0, s57
	s_nop 0
	global_load_lds_dwordx4 v[154:155], off
	s_mov_b32 m0, s58
	s_nop 0
	global_load_lds_dwordx4 v[236:237], off
	s_waitcnt vmcnt(8)
	s_waitcnt lgkmcnt(0)
	s_barrier
	s_setprio 1
	v_mfma_f32_16x16x32_bf16 v[64:67], v[146:149], v[196:199], v[64:67]
	v_mfma_f32_16x16x32_bf16 v[64:67], v[150:153], v[200:203], v[64:67]
	v_mfma_f32_16x16x32_bf16 v[60:63], v[172:175], v[196:199], v[60:63]
	v_mfma_f32_16x16x32_bf16 v[60:63], v[176:179], v[200:203], v[60:63]
	v_mfma_f32_16x16x32_bf16 v[44:47], v[172:175], v[204:207], v[44:47]
	v_mfma_f32_16x16x32_bf16 v[44:47], v[176:179], v[208:211], v[44:47]
	v_mfma_f32_16x16x32_bf16 v[48:51], v[146:149], v[204:207], v[48:51]
	v_mfma_f32_16x16x32_bf16 v[48:51], v[150:153], v[208:211], v[48:51]
	v_mfma_f32_16x16x32_bf16 v[32:35], v[146:149], v[212:215], v[32:35]
	v_mfma_f32_16x16x32_bf16 v[32:35], v[150:153], v[216:219], v[32:35]
	v_mfma_f32_16x16x32_bf16 v[28:31], v[172:175], v[212:215], v[28:31]
	v_mfma_f32_16x16x32_bf16 v[28:31], v[176:179], v[216:219], v[28:31]
	v_mfma_f32_16x16x32_bf16 v[12:15], v[172:175], v[228:231], v[12:15]
	v_mfma_f32_16x16x32_bf16 v[12:15], v[176:179], v[232:235], v[12:15]
	v_mfma_f32_16x16x32_bf16 v[16:19], v[146:149], v[228:231], v[16:19]
	v_mfma_f32_16x16x32_bf16 v[16:19], v[150:153], v[232:235], v[16:19]
	v_mfma_f32_16x16x32_bf16 v[56:59], v[180:183], v[196:199], v[56:59]
	v_mfma_f32_16x16x32_bf16 v[56:59], v[184:187], v[200:203], v[56:59]
	v_mfma_f32_16x16x32_bf16 v[52:55], v[188:191], v[196:199], v[52:55]
	v_mfma_f32_16x16x32_bf16 v[52:55], v[192:195], v[200:203], v[52:55]
	v_mfma_f32_16x16x32_bf16 v[36:39], v[188:191], v[204:207], v[36:39]
	v_mfma_f32_16x16x32_bf16 v[36:39], v[192:195], v[208:211], v[36:39]
	v_mfma_f32_16x16x32_bf16 v[40:43], v[180:183], v[204:207], v[40:43]
	v_mfma_f32_16x16x32_bf16 v[40:43], v[184:187], v[208:211], v[40:43]
	v_mfma_f32_16x16x32_bf16 v[24:27], v[180:183], v[212:215], v[24:27]
	v_mfma_f32_16x16x32_bf16 v[24:27], v[184:187], v[216:219], v[24:27]
	v_mfma_f32_16x16x32_bf16 v[20:23], v[188:191], v[212:215], v[20:23]
	v_mfma_f32_16x16x32_bf16 v[20:23], v[192:195], v[216:219], v[20:23]
	v_mfma_f32_16x16x32_bf16 v[4:7], v[188:191], v[228:231], v[4:7]
	v_mfma_f32_16x16x32_bf16 v[4:7], v[192:195], v[232:235], v[4:7]
	v_mfma_f32_16x16x32_bf16 v[8:11], v[180:183], v[228:231], v[8:11]
	v_mfma_f32_16x16x32_bf16 v[8:11], v[184:187], v[232:235], v[8:11]
	s_setprio 0
	s_barrier
	s_add_i32 s52, 0, 0x18000
	v_add_u32_e32 v145, s52, v142
	s_add_i32 s53, 0, 0x1c000
	ds_read_b128 v[146:149], v145
	ds_read_b128 v[150:153], v145 offset:1024
	ds_read_b128 v[172:175], v145 offset:2048
	ds_read_b128 v[176:179], v145 offset:3072
	v_add_u32_e32 v145, s53, v142
	ds_read_b128 v[180:183], v145
	ds_read_b128 v[184:187], v145 offset:1024
	ds_read_b128 v[188:191], v145 offset:2048
	ds_read_b128 v[192:195], v145 offset:3072
	s_add_u32 s54, s54, 0x80000
	s_addc_u32 s55, s55, 0
	s_mov_b32 m0, s59
	v_lshl_add_u64 v[238:239], s[54:55], 0, v[136:137]
	ds_read_b128 v[196:199], v144 offset:32768
	ds_read_b128 v[200:203], v144 offset:33792
	ds_read_b128 v[204:207], v144 offset:34816
	ds_read_b128 v[208:211], v144 offset:35840
	ds_read_b128 v[212:215], v144 offset:36864
	ds_read_b128 v[216:219], v144 offset:37888
	ds_read_b128 v[228:231], v144 offset:38912
	ds_read_b128 v[232:235], v144 offset:39936
	global_load_lds_dwordx4 v[238:239], off
	v_lshl_add_u64 v[238:239], s[54:55], 0, v[132:133]
	s_mov_b32 m0, s60
	s_nop 0
	global_load_lds_dwordx4 v[238:239], off
	s_waitcnt vmcnt(8)
	s_waitcnt lgkmcnt(0)
	s_barrier
	s_setprio 1
	v_mfma_f32_16x16x32_bf16 v[128:131], v[146:149], v[196:199], v[128:131]
	v_mfma_f32_16x16x32_bf16 v[128:131], v[150:153], v[200:203], v[128:131]
	v_mfma_f32_16x16x32_bf16 v[124:127], v[172:175], v[196:199], v[124:127]
	v_mfma_f32_16x16x32_bf16 v[124:127], v[176:179], v[200:203], v[124:127]
	v_mfma_f32_16x16x32_bf16 v[108:111], v[172:175], v[204:207], v[108:111]
	v_mfma_f32_16x16x32_bf16 v[108:111], v[176:179], v[208:211], v[108:111]
	v_mfma_f32_16x16x32_bf16 v[112:115], v[146:149], v[204:207], v[112:115]
	v_mfma_f32_16x16x32_bf16 v[112:115], v[150:153], v[208:211], v[112:115]
	v_mfma_f32_16x16x32_bf16 v[96:99], v[146:149], v[212:215], v[96:99]
	v_mfma_f32_16x16x32_bf16 v[96:99], v[150:153], v[216:219], v[96:99]
	v_mfma_f32_16x16x32_bf16 v[92:95], v[172:175], v[212:215], v[92:95]
	v_mfma_f32_16x16x32_bf16 v[92:95], v[176:179], v[216:219], v[92:95]
	v_mfma_f32_16x16x32_bf16 v[76:79], v[172:175], v[228:231], v[76:79]
	v_mfma_f32_16x16x32_bf16 v[76:79], v[176:179], v[232:235], v[76:79]
	v_mfma_f32_16x16x32_bf16 v[80:83], v[146:149], v[228:231], v[80:83]
	v_mfma_f32_16x16x32_bf16 v[80:83], v[150:153], v[232:235], v[80:83]
	v_mfma_f32_16x16x32_bf16 v[120:123], v[180:183], v[196:199], v[120:123]
	v_mfma_f32_16x16x32_bf16 v[120:123], v[184:187], v[200:203], v[120:123]
	v_mfma_f32_16x16x32_bf16 v[116:119], v[188:191], v[196:199], v[116:119]
	v_mfma_f32_16x16x32_bf16 v[116:119], v[192:195], v[200:203], v[116:119]
	v_mfma_f32_16x16x32_bf16 v[100:103], v[188:191], v[204:207], v[100:103]
	v_mfma_f32_16x16x32_bf16 v[100:103], v[192:195], v[208:211], v[100:103]
	v_mfma_f32_16x16x32_bf16 v[104:107], v[180:183], v[204:207], v[104:107]
	v_mfma_f32_16x16x32_bf16 v[104:107], v[184:187], v[208:211], v[104:107]
	v_mfma_f32_16x16x32_bf16 v[88:91], v[180:183], v[212:215], v[88:91]
	v_mfma_f32_16x16x32_bf16 v[88:91], v[184:187], v[216:219], v[88:91]
	v_mfma_f32_16x16x32_bf16 v[84:87], v[188:191], v[212:215], v[84:87]
	v_mfma_f32_16x16x32_bf16 v[84:87], v[192:195], v[216:219], v[84:87]
	v_mfma_f32_16x16x32_bf16 v[68:71], v[188:191], v[228:231], v[68:71]
	v_mfma_f32_16x16x32_bf16 v[68:71], v[192:195], v[232:235], v[68:71]
	v_mfma_f32_16x16x32_bf16 v[72:75], v[180:183], v[228:231], v[72:75]
	v_mfma_f32_16x16x32_bf16 v[72:75], v[184:187], v[232:235], v[72:75]
	s_setprio 0
	s_barrier
	s_add_u32 s54, s34, 0x160000
	s_addc_u32 s55, s35, 0
	s_add_i32 s52, s52, s19
	v_lshl_add_u64 v[238:239], s[54:55], 0, v[134:135]
	s_mov_b32 m0, s52
	ds_read_b128 v[196:199], v144 offset:49152
	ds_read_b128 v[200:203], v144 offset:50176
	ds_read_b128 v[204:207], v144 offset:51200
	ds_read_b128 v[208:211], v144 offset:52224
	ds_read_b128 v[212:215], v144 offset:53248
	ds_read_b128 v[216:219], v144 offset:54272
	ds_read_b128 v[228:231], v144 offset:55296
	ds_read_b128 v[232:235], v144 offset:56320
	global_load_lds_dwordx4 v[238:239], off
	s_add_i32 m0, s52, 0x2000
	s_add_u32 s34, s34, 0x164000
	v_lshl_add_u64 v[238:239], s[54:55], 0, v[0:1]
	s_addc_u32 s35, s35, 0
	s_add_i32 s52, s53, s19
	global_load_lds_dwordx4 v[238:239], off
	v_lshl_add_u64 v[238:239], s[34:35], 0, v[134:135]
	s_mov_b32 m0, s52
	v_lshl_add_u64 v[154:155], v[154:155], 0, s[14:15]
	global_load_lds_dwordx4 v[238:239], off
	v_lshl_add_u64 v[238:239], s[34:35], 0, v[0:1]
	s_add_i32 m0, s52, 0x2000
	s_nop 0
	global_load_lds_dwordx4 v[238:239], off
	s_mov_b32 m0, s61
	s_nop 0
	global_load_lds_dwordx4 v[154:155], off
	v_lshl_add_u64 v[154:155], v[236:237], 0, s[14:15]
	s_mov_b32 m0, s62
	s_nop 0
	global_load_lds_dwordx4 v[154:155], off
	s_waitcnt vmcnt(8)
	s_waitcnt lgkmcnt(0)
	s_barrier
	s_setprio 1
	v_mfma_f32_16x16x32_bf16 v[64:67], v[146:149], v[196:199], v[64:67]
	v_mfma_f32_16x16x32_bf16 v[64:67], v[150:153], v[200:203], v[64:67]
	v_mfma_f32_16x16x32_bf16 v[60:63], v[172:175], v[196:199], v[60:63]
	v_mfma_f32_16x16x32_bf16 v[60:63], v[176:179], v[200:203], v[60:63]
	v_mfma_f32_16x16x32_bf16 v[44:47], v[172:175], v[204:207], v[44:47]
	v_mfma_f32_16x16x32_bf16 v[44:47], v[176:179], v[208:211], v[44:47]
	v_mfma_f32_16x16x32_bf16 v[48:51], v[146:149], v[204:207], v[48:51]
	v_mfma_f32_16x16x32_bf16 v[48:51], v[150:153], v[208:211], v[48:51]
	v_mfma_f32_16x16x32_bf16 v[32:35], v[146:149], v[212:215], v[32:35]
	v_mfma_f32_16x16x32_bf16 v[32:35], v[150:153], v[216:219], v[32:35]
	v_mfma_f32_16x16x32_bf16 v[28:31], v[172:175], v[212:215], v[28:31]
	v_mfma_f32_16x16x32_bf16 v[28:31], v[176:179], v[216:219], v[28:31]
	v_mfma_f32_16x16x32_bf16 v[12:15], v[172:175], v[228:231], v[12:15]
	v_mfma_f32_16x16x32_bf16 v[12:15], v[176:179], v[232:235], v[12:15]
	v_mfma_f32_16x16x32_bf16 v[16:19], v[146:149], v[228:231], v[16:19]
	v_mfma_f32_16x16x32_bf16 v[16:19], v[150:153], v[232:235], v[16:19]
	v_mfma_f32_16x16x32_bf16 v[56:59], v[180:183], v[196:199], v[56:59]
	v_mfma_f32_16x16x32_bf16 v[56:59], v[184:187], v[200:203], v[56:59]
	v_mfma_f32_16x16x32_bf16 v[52:55], v[188:191], v[196:199], v[52:55]
	v_mfma_f32_16x16x32_bf16 v[52:55], v[192:195], v[200:203], v[52:55]
	v_mfma_f32_16x16x32_bf16 v[36:39], v[188:191], v[204:207], v[36:39]
	v_mfma_f32_16x16x32_bf16 v[36:39], v[192:195], v[208:211], v[36:39]
	v_mfma_f32_16x16x32_bf16 v[40:43], v[180:183], v[204:207], v[40:43]
	v_mfma_f32_16x16x32_bf16 v[40:43], v[184:187], v[208:211], v[40:43]
	v_mfma_f32_16x16x32_bf16 v[24:27], v[180:183], v[212:215], v[24:27]
	v_mfma_f32_16x16x32_bf16 v[24:27], v[184:187], v[216:219], v[24:27]
	v_mfma_f32_16x16x32_bf16 v[20:23], v[188:191], v[212:215], v[20:23]
	v_mfma_f32_16x16x32_bf16 v[20:23], v[192:195], v[216:219], v[20:23]
	v_mfma_f32_16x16x32_bf16 v[4:7], v[188:191], v[228:231], v[4:7]
	v_mfma_f32_16x16x32_bf16 v[4:7], v[192:195], v[232:235], v[4:7]
	v_mfma_f32_16x16x32_bf16 v[8:11], v[180:183], v[228:231], v[8:11]
	v_mfma_f32_16x16x32_bf16 v[8:11], v[184:187], v[232:235], v[8:11]
	s_setprio 0
	s_barrier
	s_add_i32 s77, s77, 2
	s_add_u32 s71, s71, 0x2c0000
	s_addc_u32 s76, s76, 0
	s_add_u32 s50, s50, 0x100
	s_addc_u32 s51, s51, 0
	s_cmp_gt_u32 s77, 29
	s_cbranch_scc0 .LBB0_169
	s_and_b64 vcc, exec, s[28:29]
	s_cbranch_vccz .LBB0_172
	s_barrier

.LBB0_243:
	s_add_u32 s34, s44, 0xfff80080
	s_addc_u32 s35, s45, -1
	s_add_i32 s52, 0, 0x10000
	s_cmp_eq_u32 vcc_hi, 28
	s_cselect_b32 s47, s36, s35
	s_cselect_b32 s46, s37, s34
	s_cselect_b32 s35, s55, vcc_lo
	s_cselect_b32 s34, s57, s63
	s_add_i32 s68, 0, 0x14000
	v_add_u32_e32 v144, s52, v155
	v_add_u32_e32 v180, s68, v155
	ds_read_b128 v[132:135], v144
	ds_read_b128 v[136:139], v144 offset:1024
	ds_read_b128 v[140:143], v144 offset:2048
	ds_read_b128 v[144:147], v144 offset:3072
	ds_read_b128 v[176:179], v180
	ds_read_b128 v[182:185], v180 offset:1024
	ds_read_b128 v[186:189], v180 offset:2048
	ds_read_b128 v[190:193], v180 offset:3072
	v_lshl_add_u64 v[218:219], s[44:45], 0, v[172:173]
	s_add_i32 m0, s69, 0xc000
	ds_read_b128 v[194:197], v181
	ds_read_b128 v[198:201], v181 offset:1024
	ds_read_b128 v[202:205], v181 offset:2048
	ds_read_b128 v[206:209], v181 offset:3072
	ds_read_b128 v[210:213], v181 offset:4096
	ds_read_b128 v[214:217], v181 offset:5120
	ds_read_b128 v[228:231], v181 offset:6144
	ds_read_b128 v[232:235], v181 offset:7168
	global_load_lds_dwordx4 v[218:219], off
	v_lshl_add_u64 v[218:219], s[44:45], 0, v[174:175]
	s_add_i32 m0, s69, 0xe000
	s_nop 0
	global_load_lds_dwordx4 v[218:219], off
	s_waitcnt vmcnt(8)
	s_waitcnt lgkmcnt(0)
	s_barrier
	s_setprio 1
	v_mfma_f32_16x16x32_bf16 v[128:131], v[132:135], v[194:197], v[128:131]
	v_mfma_f32_16x16x32_bf16 v[128:131], v[136:139], v[198:201], v[128:131]
	v_mfma_f32_16x16x32_bf16 v[124:127], v[140:143], v[194:197], v[124:127]
	v_mfma_f32_16x16x32_bf16 v[124:127], v[144:147], v[198:201], v[124:127]
	v_mfma_f32_16x16x32_bf16 v[108:111], v[140:143], v[202:205], v[108:111]
	v_mfma_f32_16x16x32_bf16 v[108:111], v[144:147], v[206:209], v[108:111]
	v_mfma_f32_16x16x32_bf16 v[112:115], v[132:135], v[202:205], v[112:115]
	v_mfma_f32_16x16x32_bf16 v[112:115], v[136:139], v[206:209], v[112:115]
	v_mfma_f32_16x16x32_bf16 v[96:99], v[132:135], v[210:213], v[96:99]
	v_mfma_f32_16x16x32_bf16 v[96:99], v[136:139], v[214:217], v[96:99]
	v_mfma_f32_16x16x32_bf16 v[92:95], v[140:143], v[210:213], v[92:95]
	v_mfma_f32_16x16x32_bf16 v[92:95], v[144:147], v[214:217], v[92:95]
	v_mfma_f32_16x16x32_bf16 v[76:79], v[140:143], v[228:231], v[76:79]
	v_mfma_f32_16x16x32_bf16 v[76:79], v[144:147], v[232:235], v[76:79]
	v_mfma_f32_16x16x32_bf16 v[80:83], v[132:135], v[228:231], v[80:83]
	v_mfma_f32_16x16x32_bf16 v[80:83], v[136:139], v[232:235], v[80:83]
	v_mfma_f32_16x16x32_bf16 v[120:123], v[176:179], v[194:197], v[120:123]
	v_mfma_f32_16x16x32_bf16 v[120:123], v[182:185], v[198:201], v[120:123]
	v_mfma_f32_16x16x32_bf16 v[116:119], v[186:189], v[194:197], v[116:119]
	v_mfma_f32_16x16x32_bf16 v[116:119], v[190:193], v[198:201], v[116:119]
	v_mfma_f32_16x16x32_bf16 v[100:103], v[186:189], v[202:205], v[100:103]
	v_mfma_f32_16x16x32_bf16 v[100:103], v[190:193], v[206:209], v[100:103]
	v_mfma_f32_16x16x32_bf16 v[104:107], v[176:179], v[202:205], v[104:107]
	v_mfma_f32_16x16x32_bf16 v[104:107], v[182:185], v[206:209], v[104:107]
	v_mfma_f32_16x16x32_bf16 v[88:91], v[176:179], v[210:213], v[88:91]
	v_mfma_f32_16x16x32_bf16 v[88:91], v[182:185], v[214:217], v[88:91]
	v_mfma_f32_16x16x32_bf16 v[84:87], v[186:189], v[210:213], v[84:87]
	v_mfma_f32_16x16x32_bf16 v[84:87], v[190:193], v[214:217], v[84:87]
	v_mfma_f32_16x16x32_bf16 v[68:71], v[186:189], v[228:231], v[68:71]
	v_mfma_f32_16x16x32_bf16 v[68:71], v[190:193], v[232:235], v[68:71]
	v_mfma_f32_16x16x32_bf16 v[72:75], v[176:179], v[228:231], v[72:75]
	v_mfma_f32_16x16x32_bf16 v[72:75], v[182:185], v[232:235], v[72:75]
	s_setprio 0
	s_barrier
	s_add_i32 s52, s52, s2
	v_lshl_add_u64 v[218:219], s[34:35], 0, v[150:151]
	s_mov_b32 m0, s52
	ds_read_b128 v[194:197], v181 offset:16384
	ds_read_b128 v[198:201], v181 offset:17408
	ds_read_b128 v[202:205], v181 offset:18432
	ds_read_b128 v[206:209], v181 offset:19456
	ds_read_b128 v[210:213], v181 offset:20480
	ds_read_b128 v[214:217], v181 offset:21504
	ds_read_b128 v[228:231], v181 offset:22528
	ds_read_b128 v[232:235], v181 offset:23552
	global_load_lds_dwordx4 v[218:219], off
	s_add_i32 m0, s52, 0x2000
	s_add_u32 s52, s34, 0x4000
	v_lshl_add_u64 v[218:219], s[34:35], 0, v[0:1]
	s_addc_u32 s53, s35, 0
	s_add_i32 s68, s68, s2
	global_load_lds_dwordx4 v[218:219], off
	v_lshl_add_u64 v[218:219], s[52:53], 0, v[150:151]
	s_mov_b32 m0, s68
	v_lshl_add_u64 v[236:237], s[46:47], 0, v[148:149]
	global_load_lds_dwordx4 v[218:219], off
	v_lshl_add_u64 v[218:219], s[52:53], 0, v[0:1]
	s_add_i32 m0, s68, 0x2000
	s_nop 0
	global_load_lds_dwordx4 v[218:219], off
	v_lshl_add_u64 v[218:219], s[46:47], 0, v[152:153]
	s_mov_b32 m0, s69
	s_nop 0
	global_load_lds_dwordx4 v[218:219], off
	s_mov_b32 m0, s71
	s_nop 0
	global_load_lds_dwordx4 v[236:237], off
	s_waitcnt vmcnt(8)
	s_waitcnt lgkmcnt(0)
	s_barrier
	s_setprio 1
	v_mfma_f32_16x16x32_bf16 v[64:67], v[132:135], v[194:197], v[64:67]
	v_mfma_f32_16x16x32_bf16 v[64:67], v[136:139], v[198:201], v[64:67]
	v_mfma_f32_16x16x32_bf16 v[60:63], v[140:143], v[194:197], v[60:63]
	v_mfma_f32_16x16x32_bf16 v[60:63], v[144:147], v[198:201], v[60:63]
	v_mfma_f32_16x16x32_bf16 v[44:47], v[140:143], v[202:205], v[44:47]
	v_mfma_f32_16x16x32_bf16 v[44:47], v[144:147], v[206:209], v[44:47]
	v_mfma_f32_16x16x32_bf16 v[48:51], v[132:135], v[202:205], v[48:51]
	v_mfma_f32_16x16x32_bf16 v[48:51], v[136:139], v[206:209], v[48:51]
	v_mfma_f32_16x16x32_bf16 v[32:35], v[132:135], v[210:213], v[32:35]
	v_mfma_f32_16x16x32_bf16 v[32:35], v[136:139], v[214:217], v[32:35]
	v_mfma_f32_16x16x32_bf16 v[28:31], v[140:143], v[210:213], v[28:31]
	v_mfma_f32_16x16x32_bf16 v[28:31], v[144:147], v[214:217], v[28:31]
	v_mfma_f32_16x16x32_bf16 v[12:15], v[140:143], v[228:231], v[12:15]
	v_mfma_f32_16x16x32_bf16 v[12:15], v[144:147], v[232:235], v[12:15]
	v_mfma_f32_16x16x32_bf16 v[16:19], v[132:135], v[228:231], v[16:19]
	v_mfma_f32_16x16x32_bf16 v[16:19], v[136:139], v[232:235], v[16:19]
	v_mfma_f32_16x16x32_bf16 v[56:59], v[176:179], v[194:197], v[56:59]
	v_mfma_f32_16x16x32_bf16 v[56:59], v[182:185], v[198:201], v[56:59]
	v_mfma_f32_16x16x32_bf16 v[52:55], v[186:189], v[194:197], v[52:55]
	v_mfma_f32_16x16x32_bf16 v[52:55], v[190:193], v[198:201], v[52:55]
	v_mfma_f32_16x16x32_bf16 v[36:39], v[186:189], v[202:205], v[36:39]
	v_mfma_f32_16x16x32_bf16 v[36:39], v[190:193], v[206:209], v[36:39]
	v_mfma_f32_16x16x32_bf16 v[40:43], v[176:179], v[202:205], v[40:43]
	v_mfma_f32_16x16x32_bf16 v[40:43], v[182:185], v[206:209], v[40:43]
	v_mfma_f32_16x16x32_bf16 v[24:27], v[176:179], v[210:213], v[24:27]
	v_mfma_f32_16x16x32_bf16 v[24:27], v[182:185], v[214:217], v[24:27]
	v_mfma_f32_16x16x32_bf16 v[20:23], v[186:189], v[210:213], v[20:23]
	v_mfma_f32_16x16x32_bf16 v[20:23], v[190:193], v[214:217], v[20:23]
	v_mfma_f32_16x16x32_bf16 v[4:7], v[186:189], v[228:231], v[4:7]
	v_mfma_f32_16x16x32_bf16 v[4:7], v[190:193], v[232:235], v[4:7]
	v_mfma_f32_16x16x32_bf16 v[8:11], v[176:179], v[228:231], v[8:11]
	v_mfma_f32_16x16x32_bf16 v[8:11], v[182:185], v[232:235], v[8:11]
	s_setprio 0
	s_barrier
	s_add_i32 s52, 0, 0x18000
	s_add_i32 s53, 0, 0x1c000
	v_add_u32_e32 v144, s52, v155
	v_add_u32_e32 v180, s53, v155
	ds_read_b128 v[132:135], v144
	ds_read_b128 v[136:139], v144 offset:1024
	ds_read_b128 v[140:143], v144 offset:2048
	ds_read_b128 v[144:147], v144 offset:3072
	ds_read_b128 v[176:179], v180
	ds_read_b128 v[182:185], v180 offset:1024
	ds_read_b128 v[186:189], v180 offset:2048
	ds_read_b128 v[190:193], v180 offset:3072
	s_add_u32 s46, s46, 0x80000
	s_addc_u32 s47, s47, 0
	s_mov_b32 m0, s88
	v_lshl_add_u64 v[238:239], s[46:47], 0, v[152:153]
	ds_read_b128 v[194:197], v181 offset:32768
	ds_read_b128 v[198:201], v181 offset:33792
	ds_read_b128 v[202:205], v181 offset:34816
	ds_read_b128 v[206:209], v181 offset:35840
	ds_read_b128 v[210:213], v181 offset:36864
	ds_read_b128 v[214:217], v181 offset:37888
	ds_read_b128 v[228:231], v181 offset:38912
	ds_read_b128 v[232:235], v181 offset:39936
	global_load_lds_dwordx4 v[238:239], off
	v_lshl_add_u64 v[238:239], s[46:47], 0, v[148:149]
	s_mov_b32 m0, s96
	s_nop 0
	global_load_lds_dwordx4 v[238:239], off
	s_waitcnt vmcnt(8)
	s_waitcnt lgkmcnt(0)
	s_barrier
	s_setprio 1
	v_mfma_f32_16x16x32_bf16 v[128:131], v[132:135], v[194:197], v[128:131]
	v_mfma_f32_16x16x32_bf16 v[128:131], v[136:139], v[198:201], v[128:131]
	v_mfma_f32_16x16x32_bf16 v[124:127], v[140:143], v[194:197], v[124:127]
	v_mfma_f32_16x16x32_bf16 v[124:127], v[144:147], v[198:201], v[124:127]
	v_mfma_f32_16x16x32_bf16 v[108:111], v[140:143], v[202:205], v[108:111]
	v_mfma_f32_16x16x32_bf16 v[108:111], v[144:147], v[206:209], v[108:111]
	v_mfma_f32_16x16x32_bf16 v[112:115], v[132:135], v[202:205], v[112:115]
	v_mfma_f32_16x16x32_bf16 v[112:115], v[136:139], v[206:209], v[112:115]
	v_mfma_f32_16x16x32_bf16 v[96:99], v[132:135], v[210:213], v[96:99]
	v_mfma_f32_16x16x32_bf16 v[96:99], v[136:139], v[214:217], v[96:99]
	v_mfma_f32_16x16x32_bf16 v[92:95], v[140:143], v[210:213], v[92:95]
	v_mfma_f32_16x16x32_bf16 v[92:95], v[144:147], v[214:217], v[92:95]
	v_mfma_f32_16x16x32_bf16 v[76:79], v[140:143], v[228:231], v[76:79]
	v_mfma_f32_16x16x32_bf16 v[76:79], v[144:147], v[232:235], v[76:79]
	v_mfma_f32_16x16x32_bf16 v[80:83], v[132:135], v[228:231], v[80:83]
	v_mfma_f32_16x16x32_bf16 v[80:83], v[136:139], v[232:235], v[80:83]
	v_mfma_f32_16x16x32_bf16 v[120:123], v[176:179], v[194:197], v[120:123]
	v_mfma_f32_16x16x32_bf16 v[120:123], v[182:185], v[198:201], v[120:123]
	v_mfma_f32_16x16x32_bf16 v[116:119], v[186:189], v[194:197], v[116:119]
	v_mfma_f32_16x16x32_bf16 v[116:119], v[190:193], v[198:201], v[116:119]
	v_mfma_f32_16x16x32_bf16 v[100:103], v[186:189], v[202:205], v[100:103]
	v_mfma_f32_16x16x32_bf16 v[100:103], v[190:193], v[206:209], v[100:103]
	v_mfma_f32_16x16x32_bf16 v[104:107], v[176:179], v[202:205], v[104:107]
	v_mfma_f32_16x16x32_bf16 v[104:107], v[182:185], v[206:209], v[104:107]
	v_mfma_f32_16x16x32_bf16 v[88:91], v[176:179], v[210:213], v[88:91]
	v_mfma_f32_16x16x32_bf16 v[88:91], v[182:185], v[214:217], v[88:91]
	v_mfma_f32_16x16x32_bf16 v[84:87], v[186:189], v[210:213], v[84:87]
	v_mfma_f32_16x16x32_bf16 v[84:87], v[190:193], v[214:217], v[84:87]
	v_mfma_f32_16x16x32_bf16 v[68:71], v[186:189], v[228:231], v[68:71]
	v_mfma_f32_16x16x32_bf16 v[68:71], v[190:193], v[232:235], v[68:71]
	v_mfma_f32_16x16x32_bf16 v[72:75], v[176:179], v[228:231], v[72:75]
	v_mfma_f32_16x16x32_bf16 v[72:75], v[182:185], v[232:235], v[72:75]
	s_setprio 0
	s_barrier
	s_add_u32 s46, s34, 0x70000
	s_addc_u32 s47, s35, 0
	s_add_i32 s52, s52, s2
	v_lshl_add_u64 v[238:239], s[46:47], 0, v[150:151]
	s_mov_b32 m0, s52
	ds_read_b128 v[194:197], v181 offset:49152
	ds_read_b128 v[198:201], v181 offset:50176
	ds_read_b128 v[202:205], v181 offset:51200
	ds_read_b128 v[206:209], v181 offset:52224
	ds_read_b128 v[210:213], v181 offset:53248
	ds_read_b128 v[214:217], v181 offset:54272
	ds_read_b128 v[228:231], v181 offset:55296
	ds_read_b128 v[232:235], v181 offset:56320
	global_load_lds_dwordx4 v[238:239], off
	s_add_i32 m0, s52, 0x2000
	s_add_u32 s34, s34, 0x74000
	v_lshl_add_u64 v[238:239], s[46:47], 0, v[0:1]
	s_addc_u32 s35, s35, 0
	s_add_i32 s46, s53, s2
	global_load_lds_dwordx4 v[238:239], off
	v_lshl_add_u64 v[238:239], s[34:35], 0, v[150:151]
	s_mov_b32 m0, s46
	v_lshl_add_u64 v[218:219], v[218:219], 0, s[14:15]
	global_load_lds_dwordx4 v[238:239], off
	v_lshl_add_u64 v[238:239], s[34:35], 0, v[0:1]
	s_add_i32 m0, s46, 0x2000
	s_nop 0
	global_load_lds_dwordx4 v[238:239], off
	s_mov_b32 m0, s97
	s_nop 0
	global_load_lds_dwordx4 v[218:219], off
	v_lshl_add_u64 v[218:219], v[236:237], 0, s[14:15]
	s_mov_b32 m0, s76
	s_nop 0
	global_load_lds_dwordx4 v[218:219], off
	s_waitcnt vmcnt(8)
	s_waitcnt lgkmcnt(0)
	s_barrier
	s_setprio 1
	v_mfma_f32_16x16x32_bf16 v[64:67], v[132:135], v[194:197], v[64:67]
	v_mfma_f32_16x16x32_bf16 v[64:67], v[136:139], v[198:201], v[64:67]
	v_mfma_f32_16x16x32_bf16 v[60:63], v[140:143], v[194:197], v[60:63]
	v_mfma_f32_16x16x32_bf16 v[60:63], v[144:147], v[198:201], v[60:63]
	v_mfma_f32_16x16x32_bf16 v[44:47], v[140:143], v[202:205], v[44:47]
	v_mfma_f32_16x16x32_bf16 v[44:47], v[144:147], v[206:209], v[44:47]
	v_mfma_f32_16x16x32_bf16 v[48:51], v[132:135], v[202:205], v[48:51]
	v_mfma_f32_16x16x32_bf16 v[48:51], v[136:139], v[206:209], v[48:51]
	v_mfma_f32_16x16x32_bf16 v[32:35], v[132:135], v[210:213], v[32:35]
	v_mfma_f32_16x16x32_bf16 v[32:35], v[136:139], v[214:217], v[32:35]
	v_mfma_f32_16x16x32_bf16 v[28:31], v[140:143], v[210:213], v[28:31]
	v_mfma_f32_16x16x32_bf16 v[28:31], v[144:147], v[214:217], v[28:31]
	v_mfma_f32_16x16x32_bf16 v[12:15], v[140:143], v[228:231], v[12:15]
	v_mfma_f32_16x16x32_bf16 v[12:15], v[144:147], v[232:235], v[12:15]
	v_mfma_f32_16x16x32_bf16 v[16:19], v[132:135], v[228:231], v[16:19]
	v_mfma_f32_16x16x32_bf16 v[16:19], v[136:139], v[232:235], v[16:19]
	v_mfma_f32_16x16x32_bf16 v[56:59], v[176:179], v[194:197], v[56:59]
	v_mfma_f32_16x16x32_bf16 v[56:59], v[182:185], v[198:201], v[56:59]
	v_mfma_f32_16x16x32_bf16 v[52:55], v[186:189], v[194:197], v[52:55]
	v_mfma_f32_16x16x32_bf16 v[52:55], v[190:193], v[198:201], v[52:55]
	v_mfma_f32_16x16x32_bf16 v[36:39], v[186:189], v[202:205], v[36:39]
	v_mfma_f32_16x16x32_bf16 v[36:39], v[190:193], v[206:209], v[36:39]
	v_mfma_f32_16x16x32_bf16 v[40:43], v[176:179], v[202:205], v[40:43]
	v_mfma_f32_16x16x32_bf16 v[40:43], v[182:185], v[206:209], v[40:43]
	v_mfma_f32_16x16x32_bf16 v[24:27], v[176:179], v[210:213], v[24:27]
	v_mfma_f32_16x16x32_bf16 v[24:27], v[182:185], v[214:217], v[24:27]
	v_mfma_f32_16x16x32_bf16 v[20:23], v[186:189], v[210:213], v[20:23]
	v_mfma_f32_16x16x32_bf16 v[20:23], v[190:193], v[214:217], v[20:23]
	v_mfma_f32_16x16x32_bf16 v[4:7], v[186:189], v[228:231], v[4:7]
	v_mfma_f32_16x16x32_bf16 v[4:7], v[190:193], v[232:235], v[4:7]
	v_mfma_f32_16x16x32_bf16 v[8:11], v[176:179], v[228:231], v[8:11]
	v_mfma_f32_16x16x32_bf16 v[8:11], v[182:185], v[232:235], v[8:11]
	s_setprio 0
	s_barrier
	s_add_i32 vcc_hi, vcc_hi, 2
	s_add_u32 s63, s63, 0xe0000
	s_addc_u32 vcc_lo, vcc_lo, 0
	s_add_u32 s44, s44, 0x100
	s_addc_u32 s45, s45, 0
	s_cmp_gt_u32 vcc_hi, 29
	s_cbranch_scc0 .LBB0_243
	s_and_b64 vcc, exec, s[28:29]
	s_cbranch_vccz .LBB0_246
	s_barrier

.LBB0_559:
	s_add_i32 vcc_lo, s34, 2
	s_add_u32 s35, s42, 0x80
	s_addc_u32 s52, s43, 0
	s_add_i32 s53, 0, 0x10000
	s_cmp_eq_u32 s77, s34
	s_cselect_b32 s57, s51, s52
	s_cselect_b32 s56, s50, s35
	s_cselect_b32 s35, s36, s97
	s_cselect_b32 s34, s37, s49
	s_add_i32 s68, 0, 0x14000
	v_add_u32_e32 v136, s53, v200
	v_add_u32_e32 v186, s68, v200
	ds_read_b128 v[116:119], v136
	ds_read_b128 v[120:123], v136 offset:1024
	ds_read_b128 v[124:127], v136 offset:2048
	ds_read_b128 v[136:139], v136 offset:3072
	ds_read_b128 v[148:151], v186
	ds_read_b128 v[152:155], v186 offset:1024
	ds_read_b128 v[182:185], v186 offset:2048
	ds_read_b128 v[186:189], v186 offset:3072
	v_lshl_add_u64 v[198:199], s[42:43], 0, v[178:179]
	s_add_i32 m0, s59, 0xc000
	ds_read_b128 v[190:193], v202
	ds_read_b128 v[194:197], v202 offset:1024
	ds_read_b128 v[204:207], v202 offset:2048
	ds_read_b128 v[208:211], v202 offset:3072
	ds_read_b128 v[212:215], v202 offset:4096
	ds_read_b128 v[216:219], v202 offset:5120
	ds_read_b128 v[228:231], v202 offset:6144
	ds_read_b128 v[232:235], v202 offset:7168
	global_load_lds_dwordx4 v[198:199], off
	v_lshl_add_u64 v[198:199], s[42:43], 0, v[180:181]
	s_add_i32 m0, s59, 0xe000
	s_nop 0
	global_load_lds_dwordx4 v[198:199], off
	s_waitcnt vmcnt(8)
	s_waitcnt lgkmcnt(0)
	s_barrier
	s_setprio 1
	v_mfma_f32_16x16x32_bf16 v[144:147], v[116:119], v[190:193], v[144:147]
	v_mfma_f32_16x16x32_bf16 v[144:147], v[120:123], v[194:197], v[144:147]
	v_mfma_f32_16x16x32_bf16 v[140:143], v[124:127], v[190:193], v[140:143]
	v_mfma_f32_16x16x32_bf16 v[140:143], v[136:139], v[194:197], v[140:143]
	v_mfma_f32_16x16x32_bf16 v[108:111], v[124:127], v[204:207], v[108:111]
	v_mfma_f32_16x16x32_bf16 v[108:111], v[136:139], v[208:211], v[108:111]
	v_mfma_f32_16x16x32_bf16 v[112:115], v[116:119], v[204:207], v[112:115]
	v_mfma_f32_16x16x32_bf16 v[112:115], v[120:123], v[208:211], v[112:115]
	v_mfma_f32_16x16x32_bf16 v[96:99], v[116:119], v[212:215], v[96:99]
	v_mfma_f32_16x16x32_bf16 v[96:99], v[120:123], v[216:219], v[96:99]
	v_mfma_f32_16x16x32_bf16 v[92:95], v[124:127], v[212:215], v[92:95]
	v_mfma_f32_16x16x32_bf16 v[92:95], v[136:139], v[216:219], v[92:95]
	v_mfma_f32_16x16x32_bf16 v[76:79], v[124:127], v[228:231], v[76:79]
	v_mfma_f32_16x16x32_bf16 v[76:79], v[136:139], v[232:235], v[76:79]
	v_mfma_f32_16x16x32_bf16 v[80:83], v[116:119], v[228:231], v[80:83]
	v_mfma_f32_16x16x32_bf16 v[80:83], v[120:123], v[232:235], v[80:83]
	v_mfma_f32_16x16x32_bf16 v[132:135], v[148:151], v[190:193], v[132:135]
	v_mfma_f32_16x16x32_bf16 v[132:135], v[152:155], v[194:197], v[132:135]
	v_mfma_f32_16x16x32_bf16 v[128:131], v[182:185], v[190:193], v[128:131]
	v_mfma_f32_16x16x32_bf16 v[128:131], v[186:189], v[194:197], v[128:131]
	v_mfma_f32_16x16x32_bf16 v[100:103], v[182:185], v[204:207], v[100:103]
	v_mfma_f32_16x16x32_bf16 v[100:103], v[186:189], v[208:211], v[100:103]
	v_mfma_f32_16x16x32_bf16 v[104:107], v[148:151], v[204:207], v[104:107]
	v_mfma_f32_16x16x32_bf16 v[104:107], v[152:155], v[208:211], v[104:107]
	v_mfma_f32_16x16x32_bf16 v[88:91], v[148:151], v[212:215], v[88:91]
	v_mfma_f32_16x16x32_bf16 v[88:91], v[152:155], v[216:219], v[88:91]
	v_mfma_f32_16x16x32_bf16 v[84:87], v[182:185], v[212:215], v[84:87]
	v_mfma_f32_16x16x32_bf16 v[84:87], v[186:189], v[216:219], v[84:87]
	v_mfma_f32_16x16x32_bf16 v[68:71], v[182:185], v[228:231], v[68:71]
	v_mfma_f32_16x16x32_bf16 v[68:71], v[186:189], v[232:235], v[68:71]
	v_mfma_f32_16x16x32_bf16 v[72:75], v[148:151], v[228:231], v[72:75]
	v_mfma_f32_16x16x32_bf16 v[72:75], v[152:155], v[232:235], v[72:75]
	s_setprio 0
	s_barrier
	s_add_i32 s52, s53, s58
	v_lshl_add_u64 v[198:199], s[34:35], 0, v[174:175]
	s_mov_b32 m0, s52
	ds_read_b128 v[190:193], v202 offset:16384
	ds_read_b128 v[194:197], v202 offset:17408
	ds_read_b128 v[204:207], v202 offset:18432
	ds_read_b128 v[208:211], v202 offset:19456
	ds_read_b128 v[212:215], v202 offset:20480
	ds_read_b128 v[216:219], v202 offset:21504
	ds_read_b128 v[228:231], v202 offset:22528
	ds_read_b128 v[232:235], v202 offset:23552
	global_load_lds_dwordx4 v[198:199], off
	s_add_i32 m0, s52, 0x2000
	s_add_u32 s52, s34, 0x4000
	v_lshl_add_u64 v[198:199], s[34:35], 0, v[0:1]
	s_addc_u32 s53, s35, 0
	s_add_i32 s68, s68, s58
	global_load_lds_dwordx4 v[198:199], off
	v_lshl_add_u64 v[198:199], s[52:53], 0, v[174:175]
	s_mov_b32 m0, s68
	v_lshl_add_u64 v[236:237], s[56:57], 0, v[172:173]
	global_load_lds_dwordx4 v[198:199], off
	v_lshl_add_u64 v[198:199], s[52:53], 0, v[0:1]
	s_add_i32 m0, s68, 0x2000
	s_nop 0
	global_load_lds_dwordx4 v[198:199], off
	v_lshl_add_u64 v[198:199], s[56:57], 0, v[176:177]
	s_mov_b32 m0, s59
	s_nop 0
	global_load_lds_dwordx4 v[198:199], off
	s_mov_b32 m0, s60
	s_nop 0
	global_load_lds_dwordx4 v[236:237], off
	s_waitcnt vmcnt(8)
	s_waitcnt lgkmcnt(0)
	s_barrier
	s_setprio 1
	v_mfma_f32_16x16x32_bf16 v[64:67], v[116:119], v[190:193], v[64:67]
	v_mfma_f32_16x16x32_bf16 v[64:67], v[120:123], v[194:197], v[64:67]
	v_mfma_f32_16x16x32_bf16 v[60:63], v[124:127], v[190:193], v[60:63]
	v_mfma_f32_16x16x32_bf16 v[60:63], v[136:139], v[194:197], v[60:63]
	v_mfma_f32_16x16x32_bf16 v[44:47], v[124:127], v[204:207], v[44:47]
	v_mfma_f32_16x16x32_bf16 v[44:47], v[136:139], v[208:211], v[44:47]
	v_mfma_f32_16x16x32_bf16 v[48:51], v[116:119], v[204:207], v[48:51]
	v_mfma_f32_16x16x32_bf16 v[48:51], v[120:123], v[208:211], v[48:51]
	v_mfma_f32_16x16x32_bf16 v[32:35], v[116:119], v[212:215], v[32:35]
	v_mfma_f32_16x16x32_bf16 v[32:35], v[120:123], v[216:219], v[32:35]
	v_mfma_f32_16x16x32_bf16 v[28:31], v[124:127], v[212:215], v[28:31]
	v_mfma_f32_16x16x32_bf16 v[28:31], v[136:139], v[216:219], v[28:31]
	v_mfma_f32_16x16x32_bf16 v[12:15], v[124:127], v[228:231], v[12:15]
	v_mfma_f32_16x16x32_bf16 v[12:15], v[136:139], v[232:235], v[12:15]
	v_mfma_f32_16x16x32_bf16 v[16:19], v[116:119], v[228:231], v[16:19]
	v_mfma_f32_16x16x32_bf16 v[16:19], v[120:123], v[232:235], v[16:19]
	v_mfma_f32_16x16x32_bf16 v[56:59], v[148:151], v[190:193], v[56:59]
	v_mfma_f32_16x16x32_bf16 v[56:59], v[152:155], v[194:197], v[56:59]
	v_mfma_f32_16x16x32_bf16 v[52:55], v[182:185], v[190:193], v[52:55]
	v_mfma_f32_16x16x32_bf16 v[52:55], v[186:189], v[194:197], v[52:55]
	v_mfma_f32_16x16x32_bf16 v[36:39], v[182:185], v[204:207], v[36:39]
	v_mfma_f32_16x16x32_bf16 v[36:39], v[186:189], v[208:211], v[36:39]
	v_mfma_f32_16x16x32_bf16 v[40:43], v[148:151], v[204:207], v[40:43]
	v_mfma_f32_16x16x32_bf16 v[40:43], v[152:155], v[208:211], v[40:43]
	v_mfma_f32_16x16x32_bf16 v[24:27], v[148:151], v[212:215], v[24:27]
	v_mfma_f32_16x16x32_bf16 v[24:27], v[152:155], v[216:219], v[24:27]
	v_mfma_f32_16x16x32_bf16 v[20:23], v[182:185], v[212:215], v[20:23]
	v_mfma_f32_16x16x32_bf16 v[20:23], v[186:189], v[216:219], v[20:23]
	v_mfma_f32_16x16x32_bf16 v[4:7], v[182:185], v[228:231], v[4:7]
	v_mfma_f32_16x16x32_bf16 v[4:7], v[186:189], v[232:235], v[4:7]
	v_mfma_f32_16x16x32_bf16 v[8:11], v[148:151], v[228:231], v[8:11]
	v_mfma_f32_16x16x32_bf16 v[8:11], v[152:155], v[232:235], v[8:11]
	s_setprio 0
	s_barrier
	s_add_i32 s68, 0, 0x18000
	s_add_i32 vcc_hi, 0, 0x1c000
	v_add_u32_e32 v136, s68, v200
	v_add_u32_e32 v186, vcc_hi, v200
	ds_read_b128 v[116:119], v136
	ds_read_b128 v[120:123], v136 offset:1024
	ds_read_b128 v[124:127], v136 offset:2048
	ds_read_b128 v[136:139], v136 offset:3072
	ds_read_b128 v[148:151], v186
	ds_read_b128 v[152:155], v186 offset:1024
	ds_read_b128 v[182:185], v186 offset:2048
	ds_read_b128 v[186:189], v186 offset:3072
	s_add_u32 s52, s56, s26
	s_addc_u32 s53, s57, 0
	s_mov_b32 m0, s61
	v_lshl_add_u64 v[238:239], s[52:53], 0, v[176:177]
	ds_read_b128 v[190:193], v202 offset:32768
	ds_read_b128 v[194:197], v202 offset:33792
	ds_read_b128 v[204:207], v202 offset:34816
	ds_read_b128 v[208:211], v202 offset:35840
	ds_read_b128 v[212:215], v202 offset:36864
	ds_read_b128 v[216:219], v202 offset:37888
	ds_read_b128 v[228:231], v202 offset:38912
	ds_read_b128 v[232:235], v202 offset:39936
	global_load_lds_dwordx4 v[238:239], off
	v_lshl_add_u64 v[238:239], s[52:53], 0, v[172:173]
	s_mov_b32 m0, s62
	s_nop 0
	global_load_lds_dwordx4 v[238:239], off
	s_waitcnt vmcnt(8)
	s_waitcnt lgkmcnt(0)
	s_barrier
	s_setprio 1
	v_mfma_f32_16x16x32_bf16 v[144:147], v[116:119], v[190:193], v[144:147]
	v_mfma_f32_16x16x32_bf16 v[144:147], v[120:123], v[194:197], v[144:147]
	v_mfma_f32_16x16x32_bf16 v[140:143], v[124:127], v[190:193], v[140:143]
	v_mfma_f32_16x16x32_bf16 v[140:143], v[136:139], v[194:197], v[140:143]
	v_mfma_f32_16x16x32_bf16 v[108:111], v[124:127], v[204:207], v[108:111]
	v_mfma_f32_16x16x32_bf16 v[108:111], v[136:139], v[208:211], v[108:111]
	v_mfma_f32_16x16x32_bf16 v[112:115], v[116:119], v[204:207], v[112:115]
	v_mfma_f32_16x16x32_bf16 v[112:115], v[120:123], v[208:211], v[112:115]
	v_mfma_f32_16x16x32_bf16 v[96:99], v[116:119], v[212:215], v[96:99]
	v_mfma_f32_16x16x32_bf16 v[96:99], v[120:123], v[216:219], v[96:99]
	v_mfma_f32_16x16x32_bf16 v[92:95], v[124:127], v[212:215], v[92:95]
	v_mfma_f32_16x16x32_bf16 v[92:95], v[136:139], v[216:219], v[92:95]
	v_mfma_f32_16x16x32_bf16 v[76:79], v[124:127], v[228:231], v[76:79]
	v_mfma_f32_16x16x32_bf16 v[76:79], v[136:139], v[232:235], v[76:79]
	v_mfma_f32_16x16x32_bf16 v[80:83], v[116:119], v[228:231], v[80:83]
	v_mfma_f32_16x16x32_bf16 v[80:83], v[120:123], v[232:235], v[80:83]
	v_mfma_f32_16x16x32_bf16 v[132:135], v[148:151], v[190:193], v[132:135]
	v_mfma_f32_16x16x32_bf16 v[132:135], v[152:155], v[194:197], v[132:135]
	v_mfma_f32_16x16x32_bf16 v[128:131], v[182:185], v[190:193], v[128:131]
	v_mfma_f32_16x16x32_bf16 v[128:131], v[186:189], v[194:197], v[128:131]
	v_mfma_f32_16x16x32_bf16 v[100:103], v[182:185], v[204:207], v[100:103]
	v_mfma_f32_16x16x32_bf16 v[100:103], v[186:189], v[208:211], v[100:103]
	v_mfma_f32_16x16x32_bf16 v[104:107], v[148:151], v[204:207], v[104:107]
	v_mfma_f32_16x16x32_bf16 v[104:107], v[152:155], v[208:211], v[104:107]
	v_mfma_f32_16x16x32_bf16 v[88:91], v[148:151], v[212:215], v[88:91]
	v_mfma_f32_16x16x32_bf16 v[88:91], v[152:155], v[216:219], v[88:91]
	v_mfma_f32_16x16x32_bf16 v[84:87], v[182:185], v[212:215], v[84:87]
	v_mfma_f32_16x16x32_bf16 v[84:87], v[186:189], v[216:219], v[84:87]
	v_mfma_f32_16x16x32_bf16 v[68:71], v[182:185], v[228:231], v[68:71]
	v_mfma_f32_16x16x32_bf16 v[68:71], v[186:189], v[232:235], v[68:71]
	v_mfma_f32_16x16x32_bf16 v[72:75], v[148:151], v[228:231], v[72:75]
	v_mfma_f32_16x16x32_bf16 v[72:75], v[152:155], v[232:235], v[72:75]
	s_setprio 0
	s_barrier
	s_add_u32 s52, s34, 0x40000
	s_addc_u32 s53, s35, 0
	s_add_i32 s56, s68, s58
	v_lshl_add_u64 v[238:239], s[52:53], 0, v[174:175]
	s_mov_b32 m0, s56
	ds_read_b128 v[190:193], v202 offset:49152
	ds_read_b128 v[194:197], v202 offset:50176
	ds_read_b128 v[204:207], v202 offset:51200
	ds_read_b128 v[208:211], v202 offset:52224
	ds_read_b128 v[212:215], v202 offset:53248
	ds_read_b128 v[216:219], v202 offset:54272
	ds_read_b128 v[228:231], v202 offset:55296
	ds_read_b128 v[232:235], v202 offset:56320
	global_load_lds_dwordx4 v[238:239], off
	s_add_i32 m0, s56, 0x2000
	s_add_u32 s34, s34, 0x44000
	v_lshl_add_u64 v[238:239], s[52:53], 0, v[0:1]
	s_addc_u32 s35, s35, 0
	s_add_i32 s52, vcc_hi, s58
	global_load_lds_dwordx4 v[238:239], off
	v_lshl_add_u64 v[238:239], s[34:35], 0, v[174:175]
	s_mov_b32 m0, s52
	v_lshl_add_u64 v[198:199], v[198:199], 0, s[14:15]
	global_load_lds_dwordx4 v[238:239], off
	v_lshl_add_u64 v[238:239], s[34:35], 0, v[0:1]
	s_add_i32 m0, s52, 0x2000
	s_nop 0
	global_load_lds_dwordx4 v[238:239], off
	s_mov_b32 m0, s71
	s_nop 0
	global_load_lds_dwordx4 v[198:199], off
	v_lshl_add_u64 v[198:199], v[236:237], 0, s[14:15]
	s_mov_b32 m0, s76
	s_nop 0
	global_load_lds_dwordx4 v[198:199], off
	s_waitcnt vmcnt(8)
	s_waitcnt lgkmcnt(0)
	s_barrier
	s_setprio 1
	v_mfma_f32_16x16x32_bf16 v[64:67], v[116:119], v[190:193], v[64:67]
	v_mfma_f32_16x16x32_bf16 v[64:67], v[120:123], v[194:197], v[64:67]
	v_mfma_f32_16x16x32_bf16 v[60:63], v[124:127], v[190:193], v[60:63]
	v_mfma_f32_16x16x32_bf16 v[60:63], v[136:139], v[194:197], v[60:63]
	v_mfma_f32_16x16x32_bf16 v[44:47], v[124:127], v[204:207], v[44:47]
	v_mfma_f32_16x16x32_bf16 v[44:47], v[136:139], v[208:211], v[44:47]
	v_mfma_f32_16x16x32_bf16 v[48:51], v[116:119], v[204:207], v[48:51]
	v_mfma_f32_16x16x32_bf16 v[48:51], v[120:123], v[208:211], v[48:51]
	v_mfma_f32_16x16x32_bf16 v[32:35], v[116:119], v[212:215], v[32:35]
	v_mfma_f32_16x16x32_bf16 v[32:35], v[120:123], v[216:219], v[32:35]
	v_mfma_f32_16x16x32_bf16 v[28:31], v[124:127], v[212:215], v[28:31]
	v_mfma_f32_16x16x32_bf16 v[28:31], v[136:139], v[216:219], v[28:31]
	v_mfma_f32_16x16x32_bf16 v[12:15], v[124:127], v[228:231], v[12:15]
	v_mfma_f32_16x16x32_bf16 v[12:15], v[136:139], v[232:235], v[12:15]
	v_mfma_f32_16x16x32_bf16 v[16:19], v[116:119], v[228:231], v[16:19]
	v_mfma_f32_16x16x32_bf16 v[16:19], v[120:123], v[232:235], v[16:19]
	v_mfma_f32_16x16x32_bf16 v[56:59], v[148:151], v[190:193], v[56:59]
	v_mfma_f32_16x16x32_bf16 v[56:59], v[152:155], v[194:197], v[56:59]
	v_mfma_f32_16x16x32_bf16 v[52:55], v[182:185], v[190:193], v[52:55]
	v_mfma_f32_16x16x32_bf16 v[52:55], v[186:189], v[194:197], v[52:55]
	v_mfma_f32_16x16x32_bf16 v[36:39], v[182:185], v[204:207], v[36:39]
	v_mfma_f32_16x16x32_bf16 v[36:39], v[186:189], v[208:211], v[36:39]
	v_mfma_f32_16x16x32_bf16 v[40:43], v[148:151], v[204:207], v[40:43]
	v_mfma_f32_16x16x32_bf16 v[40:43], v[152:155], v[208:211], v[40:43]
	v_mfma_f32_16x16x32_bf16 v[24:27], v[148:151], v[212:215], v[24:27]
	v_mfma_f32_16x16x32_bf16 v[24:27], v[152:155], v[216:219], v[24:27]
	v_mfma_f32_16x16x32_bf16 v[20:23], v[182:185], v[212:215], v[20:23]
	v_mfma_f32_16x16x32_bf16 v[20:23], v[186:189], v[216:219], v[20:23]
	v_mfma_f32_16x16x32_bf16 v[4:7], v[182:185], v[228:231], v[4:7]
	v_mfma_f32_16x16x32_bf16 v[4:7], v[186:189], v[232:235], v[4:7]
	v_mfma_f32_16x16x32_bf16 v[8:11], v[148:151], v[228:231], v[8:11]
	v_mfma_f32_16x16x32_bf16 v[8:11], v[152:155], v[232:235], v[8:11]
	s_setprio 0
	s_barrier
	s_add_u32 s49, s49, 0x80000
	s_addc_u32 s97, s97, 0
	s_add_u32 s42, s42, 0x100
	s_addc_u32 s43, s43, 0
	s_cmp_ge_u32 vcc_lo, s69
	s_mov_b32 s34, vcc_lo
	s_cbranch_scc0 .LBB0_559
	s_and_b64 vcc, exec, s[46:47]
	s_cbranch_vccz .LBB0_562
	s_barrier
